# stick-breaking loop: the next key tile's prefetch is waited for where it is consumed, not right after issue
# speedup vs baseline: 1.0075x; 1.0013x over previous
; DI void sb_item(int item, const Args& a, int lane) {
;     ...
;     const int head = item & 7, gt = item >> 3, row0 = gt * 32, h = lane >> 5, ln = lane & 31;
;     bf16x8 qf[4];
; #pragma unroll
;     for (int ks = 0; ks < 4; ++ks) qf[ks] = ld8(SBQ + (size_t)(row0 + ln) * 512 + head * 64 + 16 * ks + 8 * h);
;     f32x16 O0, O1;
; #pragma unroll
;     for (int i = 0; i < 16; ++i) { O0[i] = 0.f; O1[i] = 0.f; }
;     float carry = 1.f;
;     const bool prompt = row0 < MP;
;     const int gt_last = prompt ? (gt & ~255) : (gt & ~1);
;     bool done = false;
;     {
;         bf16x8 kf[4], vf[2][2];
; #pragma unroll
;         for (int ks = 0; ks < 4; ++ks) kf[ks] = ld8(SBK + (size_t)(gt * 32 + ln) * 512 + head * 64 + 16 * ks + 8 * h);
; #pragma unroll
;         for (int ds = 0; ds < 2; ++ds)
; #pragma unroll
;             for (int s = 0; s < 2; ++s) vf[ds][s] = ld44(SBVT + (((size_t)(gt * 8 + head) * 4 + 2 * s) * 64 + 32 * ds + ln) * 8 + 4 * h, 512);
;     ...
;             const bool more = kt > gt_last;
;             bf16x8 kn[4], vn[2][2];
;             const int kp = more ? kt - 1 : kt;
; #pragma unroll
;             for (int ks = 0; ks < 4; ++ks) kn[ks] = ld8(SBK + (size_t)(kp * 32 + ln) * 512 + head * 64 + 16 * ks + 8 * h);
; #pragma unroll
;             for (int ds = 0; ds < 2; ++ds)
; #pragma unroll
;                 for (int s = 0; s < 2; ++s) vn[ds][s] = ld44(SBVT + (((size_t)(kp * 8 + head) * 4 + 2 * s) * 64 + 32 * ds + ln) * 8 + 4 * h, 512);
;             __builtin_amdgcn_sched_barrier(0);
;             sb_tile(O0, O1, carry, qf, kf, vf, kt == gt, lane);
; __global__ void __launch_bounds__(512, 2) fwd(Args a) {
;     ...
;                 for (;;) {
;                     unsigned k = 0;
;                     if (lane == 0) k = __hip_atomic_fetch_add(q + 64 * x, 1u, __ATOMIC_RELAXED, __HIP_MEMORY_SCOPE_AGENT);
;                     k = (unsigned)__builtin_amdgcn_readfirstlane((int)k);
;                     if (k >= (unsigned)QN) break;
;                     if (k >= (unsigned)QS && k < (unsigned)(QS + QA)) ret_passA(x * QA + (int)k - QS, ws, lane);
;                     else sb_item(k < (unsigned)QS ? (MP / 32) * 8 + x * QS + (int)k : x * QP + (int)k - (QS + QA), a, lane);
.LBB0_104:
	s_or_b64 exec, exec, s[44:45]
	v_readfirstlane_b32 s42, v0
	s_cmpk_gt_u32 s42, 0x4b7
	s_mov_b64 s[44:45], -1
	s_cbranch_scc1 .LBB0_99
	s_sub_i32 s70, s42, 64
	s_cmpk_gt_u32 s70, 0x77
	s_cbranch_scc0 .LBB0_118
	s_cmp_lt_u32 s42, 64
	s_cselect_b32 s43, s78, s65
	s_add_i32 s82, s42, s43
	s_and_b32 s75, s42, 7
	s_ashr_i32 s69, s82, 3
	s_lshl_b32 s66, s69, 5
	s_lshl_b32 s52, s75, 7
	s_cmpk_lt_i32 s69, 0x400
	s_cselect_b64 s[44:45], -1, 0
	v_or_b32_e32 v128, s66, v157
	s_and_b64 s[42:43], s[44:45], exec
	v_ashrrev_i32_e32 v129, 31, v128
	v_readlane_b32 s42, v253, 43
	v_lshlrev_b64 v[0:1], 10, v[128:129]
	v_readlane_b32 s43, v253, 44
	v_lshl_add_u64 v[2:3], s[98:99], 0, v[0:1]
	v_lshl_add_u64 v[2:3], v[2:3], 0, s[52:53]
	v_lshl_add_u64 v[0:1], s[42:43], 0, v[0:1]
	v_mov_b32_e32 v153, v161
	s_cselect_b32 s84, 0xffffff00, -2
	v_lshl_add_u64 v[0:1], v[0:1], 0, s[52:53]
	s_ashr_i32 s83, s82, 31
	v_lshl_add_u64 v[2:3], v[2:3], 0, v[152:153]
	v_lshl_add_u64 v[0:1], v[0:1], 0, v[152:153]
	s_lshl_b64 s[42:43], s[82:83], 12
	global_load_dwordx4 v[48:51], v[2:3], off
	global_load_dwordx4 v[52:55], v[2:3], off offset:32
	global_load_dwordx4 v[56:59], v[2:3], off offset:64
	global_load_dwordx4 v[60:63], v[2:3], off offset:96
	global_load_dwordx4 v[64:67], v[0:1], off
	global_load_dwordx4 v[68:71], v[0:1], off offset:32
	global_load_dwordx4 v[72:75], v[0:1], off offset:64
	global_load_dwordx4 v[76:79], v[0:1], off offset:96
	v_lshl_add_u64 v[0:1], v[140:141], 0, s[42:43]
	s_and_b32 s42, s84, s69
	s_cmp_eq_u32 s42, s69
	s_cselect_b64 s[82:83], -1, 0
	s_cmp_lg_u32 s42, s69
	s_cselect_b64 s[84:85], -1, 0
	s_cmp_lg_u64 s[84:85], 0
	s_subb_u32 s43, s69, 0
	global_load_dwordx2 v[80:81], v[0:1], off
	global_load_dwordx2 v[82:83], v[0:1], off offset:1024
	global_load_dwordx2 v[90:91], v[0:1], off offset:1536
	global_load_dwordx2 v[88:89], v[0:1], off offset:512
	global_load_dwordx2 v[84:85], v[0:1], off offset:2048
	global_load_dwordx2 v[86:87], v[0:1], off offset:3072
	global_load_dwordx2 v[94:95], v[0:1], off offset:3584
	global_load_dwordx2 v[92:93], v[0:1], off offset:2560
	v_lshl_or_b32 v0, s43, 5, v157
	s_lshl_b32 s43, s43, 3
	v_ashrrev_i32_e32 v1, 31, v0
	s_or_b32 s84, s43, s75
	v_lshl_add_u64 v[132:133], v[142:143], 0, s[52:53]
	v_lshlrev_b64 v[0:1], 10, v[0:1]
	s_ashr_i32 s85, s84, 31
	v_lshl_add_u64 v[0:1], v[132:133], 0, v[0:1]
	s_lshl_b64 s[84:85], s[84:85], 12
	global_load_dwordx4 v[32:35], v[0:1], off
	global_load_dwordx4 v[36:39], v[0:1], off offset:32
	global_load_dwordx4 v[40:43], v[0:1], off offset:64
	global_load_dwordx4 v[44:47], v[0:1], off offset:96
	v_lshl_add_u64 v[0:1], v[140:141], 0, s[84:85]
	global_load_dwordx2 v[96:97], v[0:1], off
	global_load_dwordx2 v[98:99], v[0:1], off offset:1024
	global_load_dwordx2 v[102:103], v[0:1], off offset:1536
	global_load_dwordx2 v[100:101], v[0:1], off offset:512
	global_load_dwordx2 v[108:109], v[0:1], off offset:2048
	global_load_dwordx2 v[110:111], v[0:1], off offset:3072
	global_load_dwordx2 v[106:107], v[0:1], off offset:3584
	global_load_dwordx2 v[104:105], v[0:1], off offset:2560
	v_and_b32_e32 v1, 64, v200
	v_xor_b32_e32 v0, 32, v200
	v_add_u32_e32 v1, 64, v1
	v_cmp_lt_i32_e32 vcc, v0, v1
	s_nop 1
	v_cndmask_b32_e32 v0, v200, v0, vcc
	v_lshlrev_b32_e32 v134, 2, v0
	s_waitcnt vmcnt(23)
	v_mfma_f32_32x32x16_bf16 v[0:15], v[64:67], v[48:51], 0
	s_waitcnt vmcnt(12)
	v_mfma_f32_32x32x16_bf16 v[0:15], v[68:71], v[52:55], v[0:15]
	v_mfma_f32_32x32x16_bf16 v[0:15], v[72:75], v[56:59], v[0:15]
	v_mfma_f32_32x32x16_bf16 v[0:15], v[76:79], v[60:63], v[0:15]
	s_nop 11
	v_max_f32_e64 v0, -v0, -v0
	v_min_f32_e32 v0, 0x42c80000, v0
	v_exp_f32_e32 v0, v0
	s_nop 0
	v_add_f32_e32 v16, 1.0, v0
	v_rcp_f32_e32 v18, v16
	s_nop 0
	v_mul_f32_e32 v0, v0, v18
	v_cndmask_b32_e64 v19, 1.0, v0, s[6:7]
	v_max_f32_e64 v0, -v1, -v1
	v_min_f32_e32 v0, 0x42c80000, v0
	v_exp_f32_e32 v0, v0
	s_nop 0
	v_add_f32_e32 v1, 1.0, v0
	v_rcp_f32_e32 v20, v1
	s_nop 0
	v_mul_f32_e32 v0, v0, v20
	v_cndmask_b32_e64 v21, 1.0, v0, s[8:9]
	v_max_f32_e64 v0, -v2, -v2
	v_max_f32_e64 v2, -v3, -v3
	v_min_f32_e32 v2, 0x42c80000, v2
	v_exp_f32_e32 v2, v2
	v_min_f32_e32 v0, 0x42c80000, v0
	v_exp_f32_e32 v0, v0
	v_add_f32_e32 v3, 1.0, v2
	v_rcp_f32_e32 v22, v3
	v_max_f32_e64 v3, -v4, -v4
	v_min_f32_e32 v3, 0x42c80000, v3
	v_exp_f32_e32 v3, v3
	v_add_f32_e32 v1, 1.0, v0
	v_rcp_f32_e32 v1, v1
	v_mul_f32_e32 v2, v2, v22
	v_add_f32_e32 v4, 1.0, v3
	v_rcp_f32_e32 v23, v4
	v_max_f32_e64 v4, -v5, -v5
	v_min_f32_e32 v4, 0x42c80000, v4
	v_exp_f32_e32 v4, v4
	v_mul_f32_e32 v3, v3, v23
	v_cndmask_b32_e64 v3, 1.0, v3, s[14:15]
	v_mul_f32_e32 v0, v0, v1
	v_add_f32_e32 v5, 1.0, v4
	v_rcp_f32_e32 v24, v5
	v_cndmask_b32_e64 v2, 1.0, v2, s[12:13]
	v_cndmask_b32_e64 v1, 0, v1, s[10:11]
	v_cndmask_b32_e64 v0, 1.0, v0, s[10:11]
	v_mul_f32_e32 v4, v4, v24
	v_cndmask_b32_e64 v25, 1.0, v4, s[16:17]
	v_max_f32_e64 v4, -v6, -v6
	v_min_f32_e32 v4, 0x42c80000, v4
	v_exp_f32_e32 v4, v4
	s_nop 0
	v_add_f32_e32 v5, 1.0, v4
	v_rcp_f32_e32 v30, v5
	s_nop 0
	v_mul_f32_e32 v4, v4, v30
	v_cndmask_b32_e64 v6, 1.0, v4, s[18:19]
	v_max_f32_e64 v4, -v7, -v7
	v_min_f32_e32 v4, 0x42c80000, v4
	v_exp_f32_e32 v4, v4
	s_nop 0
	v_add_f32_e32 v5, 1.0, v4
	v_rcp_f32_e32 v7, v5
	s_nop 0
	v_mul_f32_e32 v4, v4, v7
	v_cndmask_b32_e64 v16, 1.0, v4, s[20:21]
	v_max_f32_e64 v4, -v8, -v8
	v_min_f32_e32 v4, 0x42c80000, v4
	v_exp_f32_e32 v4, v4
	s_nop 0
	v_add_f32_e32 v5, 1.0, v4
	v_rcp_f32_e32 v28, v5
; #define MFMA32(a, b, c) __builtin_amdgcn_mfma_f32_32x32x16_bf16((a), (b), (c), 0, 0, 0)
; DI float ex2(float x) { return __builtin_amdgcn_exp2f(x); }
; DI void sb_tile(f32x16& O0, f32x16& O1, float& carry, const bf16x8 (&qf)[4], const bf16x8 (&kf)[4], const bf16x8 (&vf)[2][2], bool diag, int lane) {
;     ...
;     for (int g = 0; g < 4; ++g) {
;         float av[4];
; #pragma unroll
;         for (int r = 0; r < 4; ++r) {
;             const int i = 4 * g + r;
;             const float z = __builtin_fmaxf(S[i], -100.f);
;             const float t = ex2(-z);
;             float b = __builtin_amdgcn_rcpf(1.f + t), a = t * b;
;             if (diag) { const bool ok = (8 * g + 4 * h + r) < qn; b = ok ? b : 0.f; a = ok ? a : 1.f; }
;             beta[i] = b; av[r] = a;
;         }
;         ein[4 * g + 3] = 1.f; ein[4 * g + 2] = av[3]; ein[4 * g + 1] = av[3] * av[2]; ein[4 * g] = ein[4 * g + 1] * av[1]; G[g] = ein[4 * g] * av[0];
;     }
;     float Go[4], PP[4], later[4];
; #pragma unroll
;     for (int g = 0; g < 4; ++g) { Go[g] = __shfl_xor(G[g], 32); PP[g] = G[g] * Go[g]; }
;     later[3] = carry; later[2] = later[3] * PP[3]; later[1] = later[2] * PP[2]; later[0] = later[1] * PP[1];
;     carry = later[0] * PP[0];
;     f32x16 W;
; #pragma unroll
;     for (int g = 0; g < 4; ++g) {
;         const float lt = later[g] * (h == 0 ? Go[g] : 1.f);
; #pragma unroll
;         for (int r = 0; r < 4; ++r) W[4 * g + r] = beta[4 * g + r] * ein[4 * g + r] * lt;
;     }
; #pragma unroll
;     for (int s = 0; s < 2; ++s) { const bf16x8 wb = pack8(W, s); O0 = MFMA32(vf[0][s], wb, O0); O1 = MFMA32(vf[1][s], wb, O1); }
; DI void sb_item(int item, const Args& a, int lane) {
;     ...
;             sb_tile(O0, O1, carry, qf, kf, vf, kt == gt, lane);
;             asm volatile("" :: "v"(kn[0]), "v"(kn[1]), "v"(kn[2]), "v"(kn[3]), "v"(vn[0][0]), "v"(vn[0][1]), "v"(vn[1][0]), "v"(vn[1][1]));
;             if (__all(carry < SB_EXIT)) { done = true; break; }
;             if (!more) break;
; #pragma unroll
;             for (int ks = 0; ks < 4; ++ks) kf[ks] = kn[ks];
; #pragma unroll
;             for (int ds = 0; ds < 2; ++ds)
; #pragma unroll
;                 for (int s = 0; s < 2; ++s) vf[ds][s] = vn[ds][s];
	s_nop 0
	v_mul_f32_e32 v4, v4, v28
	v_cndmask_b32_e64 v17, 1.0, v4, s[38:39]
	v_max_f32_e64 v4, -v9, -v9
	v_min_f32_e32 v4, 0x42c80000, v4
	v_exp_f32_e32 v4, v4
	v_max_f32_e64 v9, -v13, -v13
	v_min_f32_e32 v9, 0x42c80000, v9
	v_exp_f32_e32 v9, v9
	v_add_f32_e32 v5, 1.0, v4
	v_rcp_f32_e32 v27, v5
	v_max_f32_e64 v5, -v11, -v11
	v_min_f32_e32 v5, 0x42c80000, v5
	v_exp_f32_e32 v5, v5
	v_mul_f32_e32 v4, v4, v27
	v_cndmask_b32_e64 v26, 1.0, v4, s[22:23]
	v_max_f32_e64 v4, -v10, -v10
	v_add_f32_e32 v8, 1.0, v5
	v_rcp_f32_e32 v29, v8
	v_min_f32_e32 v4, 0x42c80000, v4
	v_exp_f32_e32 v10, v4
	v_cndmask_b32_e64 v117, 0, v27, s[22:23]
	v_mul_f32_e32 v5, v5, v29
	v_cndmask_b32_e64 v8, 1.0, v5, s[24:25]
	v_max_f32_e64 v5, -v12, -v12
	v_add_f32_e32 v12, 1.0, v9
	v_rcp_f32_e32 v31, v12
	v_max_f32_e64 v12, -v14, -v14
	v_min_f32_e32 v12, 0x42c80000, v12
	v_exp_f32_e32 v12, v12
	v_min_f32_e32 v5, 0x42c80000, v5
	v_exp_f32_e32 v11, v5
	v_add_f32_e32 v4, 1.0, v10
	v_add_f32_e32 v13, 1.0, v12
	v_rcp_f32_e32 v116, v13
	v_max_f32_e64 v13, -v15, -v15
	v_min_f32_e32 v13, 0x42c80000, v13
	v_exp_f32_e32 v13, v13
	v_add_f32_e32 v5, 1.0, v11
	v_rcp_f32_e32 v4, v4
	v_rcp_f32_e32 v5, v5
	v_add_f32_e32 v14, 1.0, v13
	v_rcp_f32_e32 v118, v14
	v_mul_f32_e32 v12, v12, v116
	v_mul_f32_e32 v9, v9, v31
	v_cndmask_b32_e64 v12, 1.0, v12, s[34:35]
	v_mul_f32_e32 v13, v13, v118
	v_cndmask_b32_e64 v119, 1.0, v13, s[36:37]
	v_cndmask_b32_e64 v9, 1.0, v9, s[30:31]
	v_mul_f32_e32 v120, v119, v12
	v_pk_mul_f32 v[10:11], v[10:11], v[4:5]
	v_mul_f32_e32 v9, v9, v120
	v_cndmask_b32_e64 v11, 1.0, v11, s[26:27]
	v_cndmask_b32_e64 v10, 1.0, v10, s[28:29]
	v_pk_mul_f32 v[10:11], v[10:11], v[8:9]
	ds_bpermute_b32 v27, v134, v11
	v_cndmask_b32_e64 v13, 0, v29, s[24:25]
	v_cndmask_b32_e64 v4, 0, v4, s[28:29]
	v_mul_f32_e32 v12, v4, v8
	v_cndmask_b32_e64 v4, 0, v30, s[18:19]
	s_waitcnt lgkmcnt(0)
	v_pk_mul_f32 v[14:15], v[26:27], v[10:11]
	v_mul_f32_e32 v117, v117, v10
	v_mul_f32_e32 v11, v17, v14
	ds_bpermute_b32 v29, v134, v11
	v_mul_f32_e32 v10, v4, v16
	v_cndmask_b32_e64 v28, 0, v28, s[38:39]
	v_cndmask_b32_e64 v5, 0, v5, s[26:27]
	v_cndmask_b32_e64 v26, 1.0, v27, s[40:41]
	s_waitcnt lgkmcnt(0)
	v_mul_f32_e32 v17, v11, v29
	v_cndmask_b32_e64 v11, 0, v7, s[20:21]
	v_mov_b32_e32 v7, v15
	v_pk_mul_f32 v[6:7], v[16:17], v[6:7]
	v_cndmask_b32_e64 v29, 1.0, v29, s[40:41]
	v_mul_f32_e32 v4, v25, v6
	v_mul_f32_e32 v3, v3, v4
	ds_bpermute_b32 v8, v134, v3
	v_pk_mul_f32 v[112:113], v[28:29], v[14:15]
	v_mul_f32_e32 v5, v5, v9
	v_pk_mul_f32 v[114:115], v[12:13], v[112:113] op_sel:[0,1]
	v_cndmask_b32_e64 v12, 0, v24, s[16:17]
	s_waitcnt lgkmcnt(0)
	v_cndmask_b32_e64 v13, 1.0, v8, s[40:41]
	v_pk_mul_f32 v[12:13], v[12:13], v[6:7]
	v_mul_f32_e32 v3, v3, v8
	v_pk_mul_f32 v[10:11], v[10:11], v[12:13] op_sel:[0,1]
	v_pk_mul_f32 v[14:15], v[12:13], v[12:13] op_sel_hi:[0,1]
	v_mul_f32_e32 v12, v1, v2
	v_mov_b32_e32 v1, v7
	v_pk_mul_f32 v[0:1], v[2:3], v[0:1]
	v_cndmask_b32_e64 v6, 0, v23, s[14:15]
	v_mul_f32_e32 v8, v21, v0
	v_mul_f32_e32 v2, v19, v8
	ds_bpermute_b32 v3, v134, v2
	v_mul_f32_e32 v4, v6, v4
	v_mul_f32_e32 v4, v4, v13
	v_cndmask_b32_e64 v13, 0, v22, s[12:13]
	v_mul_f32_e32 v121, v26, v5
	s_waitcnt lgkmcnt(0)
	v_mul_f32_e32 v2, v2, v3
	v_mul_f32_e32 v131, v2, v1
	v_cndmask_b32_e64 v3, 1.0, v3, s[40:41]
	v_cndmask_b32_e64 v2, 0, v20, s[8:9]
	v_pk_mul_f32 v[0:1], v[2:3], v[0:1]
	v_cvt_pk_bf16_f32 v19, v10, v11
	v_pk_mul_f32 v[2:3], v[12:13], v[0:1] op_sel:[0,1]
	v_pk_mul_f32 v[6:7], v[0:1], v[0:1] op_sel_hi:[0,1]
	v_cndmask_b32_e64 v0, 0, v18, s[6:7]
	v_mul_f32_e32 v0, v0, v8
	v_mul_f32_e32 v6, v0, v1
	v_cndmask_b32_e64 v0, 0, v116, s[34:35]
	v_cndmask_b32_e64 v8, 0, v31, s[30:31]
	v_cndmask_b32_e64 v1, 0, v118, s[36:37]
	v_mul_f32_e32 v5, v8, v120
	v_mul_f32_e32 v0, v0, v119
	v_cvt_pk_bf16_f32 v16, v6, v7
	v_cvt_pk_bf16_f32 v17, v2, v3
	v_cvt_pk_bf16_f32 v18, v4, v15
	v_mul_f32_e32 v120, v26, v5
	v_pk_mul_f32 v[118:119], v[26:27], v[0:1] op_sel_hi:[0,1]
	v_mfma_f32_32x32x16_bf16 v[0:15], v[80:83], v[16:19], 0
	v_mov_b32_e32 v116, v112
	v_mul_f32_e64 v112, v116, v113
	v_mul_f32_e64 v113, v117, v113
	v_cmp_gt_f32_e32 vcc, s72, v131
	v_cvt_pk_bf16_f32 v112, v112, v113
	v_cvt_pk_bf16_f32 v113, v114, v115
	v_cvt_pk_bf16_f32 v114, v121, v120
	v_cvt_pk_bf16_f32 v115, v118, v119
	v_mfma_f32_32x32x16_bf16 v[16:31], v[88:91], v[16:19], 0
	s_cmp_eq_u64 vcc, exec
	s_cselect_b64 s[84:85], -1, 0
	s_or_b64 s[82:83], s[84:85], s[82:83]
	s_and_b64 vcc, exec, s[82:83]
	v_mfma_f32_32x32x16_bf16 v[0:15], v[84:87], v[112:115], v[0:15]
	v_mfma_f32_32x32x16_bf16 v[16:31], v[92:95], v[112:115], v[16:31]
	s_cbranch_vccnz .LBB0_109
	s_waitcnt vmcnt(0)
	v_mov_b64_e32 v[66:67], v[34:35]
	v_mov_b64_e32 v[70:71], v[38:39]
	v_mov_b64_e32 v[74:75], v[42:43]
	v_mov_b64_e32 v[78:79], v[46:47]
	s_mov_b64 s[84:85], 0
	v_mov_b64_e32 v[64:65], v[32:33]
	v_mov_b64_e32 v[68:69], v[36:37]
	v_mov_b64_e32 v[72:73], v[40:41]
	v_mov_b64_e32 v[76:77], v[44:45]
	v_mov_b32_e32 v80, v96
	v_mov_b32_e32 v81, v97
	v_mov_b32_e32 v82, v98
	v_mov_b32_e32 v83, v99
	v_mov_b32_e32 v84, v108
	v_mov_b32_e32 v85, v109
	v_mov_b32_e32 v86, v110
	v_mov_b32_e32 v87, v111
	v_mov_b32_e32 v88, v100
	v_mov_b32_e32 v89, v101
	v_mov_b32_e32 v90, v102
	v_mov_b32_e32 v91, v103
	v_mov_b32_e32 v92, v104
	v_mov_b32_e32 v93, v105
	v_mov_b32_e32 v94, v106
	v_mov_b32_e32 v95, v107
	s_xor_b64 s[82:83], s[82:83], -1
	s_andn2_b64 vcc, exec, s[82:83]
	s_cbranch_vccz .LBB0_110

; DI void sb_item(int item, const Args& a, int lane) {
;     ...
;             if (__all(carry < SB_EXIT)) { done = true; break; }
;             if (!more) break;
.LBB0_109:
	s_waitcnt vmcnt(0)
	s_xor_b64 s[82:83], s[82:83], -1
	s_andn2_b64 vcc, exec, s[82:83]
	s_cbranch_vccnz .LBB0_108

; DI float ex2(float x) { return __builtin_amdgcn_exp2f(x); }
; DI void sb_tile(f32x16& O0, f32x16& O1, float& carry, const bf16x8 (&qf)[4], const bf16x8 (&kf)[4], const bf16x8 (&vf)[2][2], bool diag, int lane) {
;     ...
;     for (int g = 0; g < 4; ++g) {
;         float av[4];
; #pragma unroll
;         for (int r = 0; r < 4; ++r) {
;             const int i = 4 * g + r;
;             const float z = __builtin_fmaxf(S[i], -100.f);
;             const float t = ex2(-z);
;             float b = __builtin_amdgcn_rcpf(1.f + t), a = t * b;
;             if (diag) { const bool ok = (8 * g + 4 * h + r) < qn; b = ok ? b : 0.f; a = ok ? a : 1.f; }
;             beta[i] = b; av[r] = a;
;         }
;         ein[4 * g + 3] = 1.f; ein[4 * g + 2] = av[3]; ein[4 * g + 1] = av[3] * av[2]; ein[4 * g] = ein[4 * g + 1] * av[1]; G[g] = ein[4 * g] * av[0];
; DI void sb_item(int item, const Args& a, int lane) {
;     ...
;             const bool more = kt > gt_last;
;             bf16x8 kn[4], vn[2][2];
;             const int kp = more ? kt - 1 : kt;
; #pragma unroll
;             for (int ks = 0; ks < 4; ++ks) kn[ks] = ld8(SBK + (size_t)(kp * 32 + ln) * 512 + head * 64 + 16 * ks + 8 * h);
; #pragma unroll
;             for (int ds = 0; ds < 2; ++ds)
; #pragma unroll
;                 for (int s = 0; s < 2; ++s) vn[ds][s] = ld44(SBVT + (((size_t)(kp * 8 + head) * 4 + 2 * s) * 64 + 32 * ds + ln) * 8 + 4 * h, 512);
;             __builtin_amdgcn_sched_barrier(0);
;             sb_tile(O0, O1, carry, qf, kf, vf, kt == gt, lane);
;             asm volatile("" :: "v"(kn[0]), "v"(kn[1]), "v"(kn[2]), "v"(kn[3]), "v"(vn[0][0]), "v"(vn[0][1]), "v"(vn[1][0]), "v"(vn[1][1]));
;             if (__all(carry < SB_EXIT)) { done = true; break; }
;             if (!more) break;
; #pragma unroll
;             for (int ks = 0; ks < 4; ++ks) kf[ks] = kn[ks];
; #pragma unroll
;             for (int ds = 0; ds < 2; ++ds)
; #pragma unroll
;                 for (int s = 0; s < 2; ++s) vf[ds][s] = vn[ds][s];
.LBB0_111:
	s_waitcnt vmcnt(0)
	v_mov_b64_e32 v[64:65], v[96:97]
	v_mov_b64_e32 v[68:69], v[100:101]
	v_mov_b64_e32 v[72:73], v[104:105]
	v_mov_b64_e32 v[76:77], v[108:109]
	v_mov_b64_e32 v[66:67], v[98:99]
	v_mov_b64_e32 v[70:71], v[102:103]
	v_mov_b64_e32 v[74:75], v[106:107]
	v_mov_b64_e32 v[78:79], v[110:111]
	v_mov_b32_e32 v80, v112
	v_mov_b32_e32 v81, v113
	v_mov_b32_e32 v82, v114
	v_mov_b32_e32 v83, v115
	v_mov_b32_e32 v84, v124
	v_mov_b32_e32 v85, v125
	v_mov_b32_e32 v86, v126
	v_mov_b32_e32 v87, v127
	v_mov_b32_e32 v88, v116
	v_mov_b32_e32 v89, v117
	v_mov_b32_e32 v90, v118
	v_mov_b32_e32 v91, v119
	v_mov_b32_e32 v92, v120
	v_mov_b32_e32 v93, v121
	v_mov_b32_e32 v94, v122
	v_mov_b32_e32 v95, v123
	s_andn2_b64 vcc, exec, s[82:83]
	s_cbranch_vccz .LBB0_114
.LBB0_112:
	s_add_i32 s52, s69, s43
	s_cmp_le_i32 s52, s42
	s_cselect_b64 s[82:83], -1, 0
	s_cmp_gt_i32 s52, s42
	s_cselect_b64 s[96:97], -1, 0
	s_cmp_lg_u64 s[96:97], 0
	s_subb_u32 s52, s52, 0
	v_lshl_or_b32 v32, s52, 5, v157
	s_lshl_b32 s52, s52, 3
	v_ashrrev_i32_e32 v33, 31, v32
	s_or_b32 s96, s52, s75
	v_lshlrev_b64 v[32:33], 10, v[32:33]
	s_ashr_i32 s97, s96, 31
	v_lshl_add_u64 v[32:33], v[132:133], 0, v[32:33]
	s_lshl_b64 s[96:97], s[96:97], 12
	global_load_dwordx4 v[96:99], v[32:33], off
	global_load_dwordx4 v[100:103], v[32:33], off offset:32
	global_load_dwordx4 v[104:107], v[32:33], off offset:64
	global_load_dwordx4 v[108:111], v[32:33], off offset:96
	v_lshl_add_u64 v[32:33], v[140:141], 0, s[96:97]
	global_load_dwordx2 v[112:113], v[32:33], off
	global_load_dwordx2 v[114:115], v[32:33], off offset:1024
	global_load_dwordx2 v[118:119], v[32:33], off offset:1536
	global_load_dwordx2 v[116:117], v[32:33], off offset:512
	global_load_dwordx2 v[124:125], v[32:33], off offset:2048
	global_load_dwordx2 v[126:127], v[32:33], off offset:3072
	global_load_dwordx2 v[122:123], v[32:33], off offset:3584
	global_load_dwordx2 v[120:121], v[32:33], off offset:2560
	v_mfma_f32_32x32x16_bf16 v[32:47], v[64:67], v[48:51], 0
	v_sub_co_u32_e64 v174, vcc, s43, 1
	s_nop 0
	v_readfirstlane_b32 s43, v174
	v_mfma_f32_32x32x16_bf16 v[32:47], v[68:71], v[52:55], v[32:47]
	v_mfma_f32_32x32x16_bf16 v[32:47], v[72:75], v[56:59], v[32:47]
	v_mfma_f32_32x32x16_bf16 v[32:47], v[76:79], v[60:63], v[32:47]
	s_nop 11
	v_max_f32_e64 v32, -v32, -v32
	v_max_f32_e64 v33, -v33, -v33
	v_min_f32_e32 v32, 0x42c80000, v32
	v_min_f32_e32 v33, 0x42c80000, v33
	v_max_f32_e64 v36, -v36, -v36
	v_exp_f32_e32 v32, v32
	v_exp_f32_e32 v33, v33
	v_min_f32_e32 v36, 0x42c80000, v36
	v_exp_f32_e32 v130, v36
	v_max_f32_e64 v34, -v34, -v34
	v_min_f32_e32 v34, 0x42c80000, v34
	v_add_f32_e32 v36, 1.0, v32
	v_add_f32_e32 v135, 1.0, v33
	v_max_f32_e64 v37, -v37, -v37
	v_exp_f32_e32 v34, v34
	v_rcp_f32_e32 v153, v36
	v_rcp_f32_e32 v135, v135
	v_min_f32_e32 v37, 0x42c80000, v37
	v_add_f32_e32 v138, 1.0, v130
	v_max_f32_e64 v35, -v35, -v35
	v_exp_f32_e32 v37, v37
	v_rcp_f32_e32 v160, v138
	v_min_f32_e32 v35, 0x42c80000, v35
	v_exp_f32_e32 v35, v35
	v_add_f32_e32 v136, 1.0, v34
	v_mul_f32_e32 v32, v32, v153
	v_mul_f32_e32 v33, v33, v135
	v_rcp_f32_e32 v155, v136
	v_cndmask_b32_e64 v36, 1.0, v32, s[6:7]
	v_cndmask_b32_e64 v136, 1.0, v33, s[8:9]
	v_max_f32_e64 v38, -v38, -v38
	v_cndmask_b32_e32 v175, v32, v36, vcc
	v_cndmask_b32_e32 v32, v33, v136, vcc
	v_mul_f32_e32 v33, v130, v160
	v_add_f32_e32 v130, 1.0, v37
	v_min_f32_e32 v38, 0x42c80000, v38
	v_rcp_f32_e32 v176, v130
	v_exp_f32_e32 v130, v38
	v_add_f32_e32 v137, 1.0, v35
	v_rcp_f32_e32 v156, v137
	v_max_f32_e64 v40, -v40, -v40
	v_add_f32_e32 v38, 1.0, v130
	v_rcp_f32_e32 v158, v38
	v_max_f32_e64 v38, -v39, -v39
	v_mul_f32_e32 v35, v35, v156
	v_min_f32_e32 v38, 0x42c80000, v38
	v_cndmask_b32_e64 v138, 1.0, v35, s[12:13]
	v_exp_f32_e32 v39, v38
	v_cndmask_b32_e32 v36, v35, v138, vcc
	v_cndmask_b32_e64 v35, 1.0, v33, s[14:15]
	v_cndmask_b32_e32 v33, v33, v35, vcc
	v_mul_f32_e32 v35, v37, v176
	v_cndmask_b32_e64 v37, 1.0, v35, s[16:17]
	v_cndmask_b32_e32 v38, v35, v37, vcc
	v_mul_f32_e32 v35, v130, v158
	v_add_f32_e32 v130, 1.0, v39
	v_min_f32_e32 v40, 0x42c80000, v40
	v_rcp_f32_e32 v159, v130
	v_exp_f32_e32 v130, v40
	v_cndmask_b32_e64 v37, 1.0, v35, s[18:19]
	v_max_f32_e64 v41, -v41, -v41
	v_cndmask_b32_e32 v40, v35, v37, vcc
	v_mul_f32_e32 v35, v39, v159
	v_add_f32_e32 v39, 1.0, v130
	v_min_f32_e32 v41, 0x42c80000, v41
	v_rcp_f32_e32 v39, v39
	v_exp_f32_e32 v41, v41
	v_max_f32_e64 v42, -v42, -v42
	v_min_f32_e32 v42, 0x42c80000, v42
	v_exp_f32_e32 v42, v42
	v_max_f32_e64 v43, -v43, -v43
	v_cndmask_b32_e64 v37, 1.0, v35, s[20:21]
	v_min_f32_e32 v43, 0x42c80000, v43
	v_cndmask_b32_e32 v136, v35, v37, vcc
	v_mul_f32_e32 v35, v130, v39
	v_add_f32_e32 v130, 1.0, v41
	v_exp_f32_e32 v138, v43
	v_max_f32_e64 v43, -v44, -v44
	v_mul_f32_e32 v34, v34, v155
	v_rcp_f32_e32 v177, v130
	v_min_f32_e32 v43, 0x42c80000, v43
	v_cndmask_b32_e64 v137, 1.0, v34, s[10:11]
	v_add_f32_e32 v130, 1.0, v42
	v_exp_f32_e32 v43, v43
	v_max_f32_e64 v44, -v45, -v45
	v_cndmask_b32_e32 v34, v34, v137, vcc
	v_rcp_f32_e32 v137, v130
	v_min_f32_e32 v44, 0x42c80000, v44
	v_cndmask_b32_e64 v37, 1.0, v35, s[38:39]
	v_exp_f32_e32 v44, v44
	v_cndmask_b32_e32 v35, v35, v37, vcc
	v_mul_f32_e32 v37, v41, v177
	v_cndmask_b32_e64 v41, 1.0, v37, s[22:23]
	v_add_f32_e32 v45, 1.0, v43
	v_cndmask_b32_e32 v130, v37, v41, vcc
	v_mul_f32_e32 v37, v42, v137
	v_add_f32_e32 v42, 1.0, v138
	v_rcp_f32_e32 v178, v45
	v_max_f32_e64 v45, -v46, -v46
	v_rcp_f32_e32 v139, v42
	v_add_f32_e32 v42, 1.0, v44
	v_min_f32_e32 v45, 0x42c80000, v45
	v_rcp_f32_e32 v179, v42
	v_exp_f32_e32 v45, v45
	v_max_f32_e64 v46, -v47, -v47
	v_min_f32_e32 v46, 0x42c80000, v46
	v_mul_f32_e32 v42, v43, v178
	v_exp_f32_e32 v46, v46
	v_cndmask_b32_e64 v43, 1.0, v42, s[26:27]
	v_cndmask_b32_e32 v42, v42, v43, vcc
	v_mul_f32_e32 v43, v44, v179
	v_add_f32_e32 v47, 1.0, v45
	v_cndmask_b32_e64 v44, 1.0, v43, s[30:31]
	v_rcp_f32_e32 v180, v47
	v_cndmask_b32_e32 v43, v43, v44, vcc
	v_add_f32_e32 v44, 1.0, v46
	v_rcp_f32_e32 v181, v44
	v_mul_f32_e32 v44, v45, v180
	v_cndmask_b32_e64 v45, 1.0, v44, s[34:35]
	v_cndmask_b32_e32 v44, v44, v45, vcc
	v_mul_f32_e32 v45, v46, v181
	v_cndmask_b32_e64 v46, 1.0, v45, s[36:37]
	v_cndmask_b32_e32 v182, v45, v46, vcc
	v_mul_f32_e32 v183, v182, v44
	v_mul_f32_e32 v184, v43, v183
	v_mul_f32_e32 v43, v42, v184
	ds_bpermute_b32 v45, v134, v43
	v_cndmask_b32_e64 v41, 1.0, v37, s[28:29]
	v_cndmask_b32_e32 v44, v37, v41, vcc
	v_mul_f32_e32 v37, v138, v139
	v_cndmask_b32_e64 v41, 1.0, v37, s[24:25]
	v_cndmask_b32_e32 v42, v37, v41, vcc
	s_waitcnt lgkmcnt(0)
; #define MFMA32(a, b, c) __builtin_amdgcn_mfma_f32_32x32x16_bf16((a), (b), (c), 0, 0, 0)
; DI void sb_tile(f32x16& O0, f32x16& O1, float& carry, const bf16x8 (&qf)[4], const bf16x8 (&kf)[4], const bf16x8 (&vf)[2][2], bool diag, int lane) {
;     ...
;     float Go[4], PP[4], later[4];
; #pragma unroll
;     for (int g = 0; g < 4; ++g) { Go[g] = __shfl_xor(G[g], 32); PP[g] = G[g] * Go[g]; }
;     later[3] = carry; later[2] = later[3] * PP[3]; later[1] = later[2] * PP[2]; later[0] = later[1] * PP[1];
;     carry = later[0] * PP[0];
;     f32x16 W;
; #pragma unroll
;     for (int g = 0; g < 4; ++g) {
;         const float lt = later[g] * (h == 0 ? Go[g] : 1.f);
; #pragma unroll
;         for (int r = 0; r < 4; ++r) W[4 * g + r] = beta[4 * g + r] * ein[4 * g + r] * lt;
;     }
; #pragma unroll
;     for (int s = 0; s < 2; ++s) { const bf16x8 wb = pack8(W, s); O0 = MFMA32(vf[0][s], wb, O0); O1 = MFMA32(vf[1][s], wb, O1); }
; DI void sb_item(int item, const Args& a, int lane) {
;     ...
;             sb_tile(O0, O1, carry, qf, kf, vf, kt == gt, lane);
;             asm volatile("" :: "v"(kn[0]), "v"(kn[1]), "v"(kn[2]), "v"(kn[3]), "v"(vn[0][0]), "v"(vn[0][1]), "v"(vn[1][0]), "v"(vn[1][1]));
;             if (__all(carry < SB_EXIT)) { done = true; break; }
;             if (!more) break;
; #pragma unroll
;             for (int ks = 0; ks < 4; ++ks) kf[ks] = kn[ks];
; #pragma unroll
;             for (int ds = 0; ds < 2; ++ds)
; #pragma unroll
;                 for (int s = 0; s < 2; ++s) vf[ds][s] = vn[ds][s];
;         }
;     }
;     if (!prompt && !done) {
	v_cndmask_b32_e64 v185, 1.0, v45, s[40:41]
	v_cndmask_b32_e64 v37, 0, v139, s[24:25]
	v_pk_mul_f32 v[44:45], v[42:43], v[44:45]
	v_cndmask_b32_e32 v47, v139, v37, vcc
	v_cndmask_b32_e64 v37, 0, v137, s[28:29]
	v_pk_mul_f32 v[138:139], v[130:131], v[44:45]
	v_cndmask_b32_e32 v37, v137, v37, vcc
	v_mul_f32_e32 v137, v35, v138
	ds_bpermute_b32 v41, v134, v137
	v_mul_f32_e32 v46, v37, v42
	v_cndmask_b32_e64 v35, 0, v177, s[22:23]
	v_cndmask_b32_e64 v37, 0, v39, s[38:39]
	v_cndmask_b32_e32 v35, v177, v35, vcc
	s_waitcnt lgkmcnt(0)
	v_cndmask_b32_e64 v43, 1.0, v41, s[40:41]
	v_cndmask_b32_e32 v42, v39, v37, vcc
	v_pk_mul_f32 v[40:41], v[136:137], v[40:41]
	v_mov_b32_e32 v39, v139
	v_mul_f32_e32 v45, v35, v44
	v_cndmask_b32_e64 v35, 0, v159, s[20:21]
	v_pk_mul_f32 v[38:39], v[38:39], v[40:41]
	v_cndmask_b32_e32 v159, v159, v35, vcc
	v_cndmask_b32_e64 v35, 0, v158, s[18:19]
	v_mul_f32_e32 v37, v33, v38
	v_cndmask_b32_e32 v44, v158, v35, vcc
	ds_bpermute_b32 v35, v134, v37
	v_cndmask_b32_e64 v33, 0, v176, s[16:17]
	v_cndmask_b32_e64 v41, 0, v160, s[14:15]
	v_mul_f32_e32 v158, v44, v136
	v_cndmask_b32_e32 v33, v176, v33, vcc
	s_waitcnt lgkmcnt(0)
	v_cndmask_b32_e64 v137, 1.0, v35, s[40:41]
	v_cndmask_b32_e32 v136, v160, v41, vcc
	v_pk_mul_f32 v[136:137], v[136:137], v[38:39]
	v_mul_f32_e32 v41, v33, v40
	v_cndmask_b32_e64 v33, 0, v156, s[12:13]
	v_pk_mul_f32 v[42:43], v[42:43], v[138:139]
	v_pk_mul_f32 v[138:139], v[158:159], v[136:137] op_sel:[0,1]
	v_cndmask_b32_e32 v159, v156, v33, vcc
	v_cndmask_b32_e64 v33, 0, v155, s[10:11]
	v_cndmask_b32_e32 v40, v155, v33, vcc
	v_pk_mul_f32 v[34:35], v[36:37], v[34:35]
	v_mov_b32_e32 v33, v39
	v_pk_mul_f32 v[38:39], v[32:33], v[34:35]
	v_cndmask_b32_e64 v32, 0, v135, s[8:9]
	v_mul_f32_e32 v130, v175, v38
	ds_bpermute_b32 v155, v134, v130
	v_cndmask_b32_e32 v35, v135, v32, vcc
	v_cndmask_b32_e64 v32, 0, v153, s[6:7]
	v_cndmask_b32_e32 v32, v153, v32, vcc
	v_mul_f32_e32 v158, v40, v36
	s_waitcnt lgkmcnt(0)
	v_cndmask_b32_e64 v33, 1.0, v155, s[40:41]
	v_pk_mul_f32 v[32:33], v[32:33], v[38:39]
	v_mul_f32_e32 v35, v35, v34
	v_cndmask_b32_e64 v34, 0, v181, s[36:37]
	v_pk_mul_f32 v[36:37], v[158:159], v[32:33] op_sel:[0,1]
	v_cndmask_b32_e32 v159, v181, v34, vcc
	v_cndmask_b32_e64 v34, 0, v180, s[34:35]
	v_cndmask_b32_e32 v38, v180, v34, vcc
	v_cndmask_b32_e64 v34, 0, v179, s[30:31]
	v_cndmask_b32_e32 v44, v179, v34, vcc
	v_mov_b32_e32 v34, v32
	v_mov_b32_e32 v40, v136
	v_pk_mul_f32 v[32:33], v[34:35], v[32:33] op_sel:[0,1]
	v_pk_mul_f32 v[34:35], v[40:41], v[136:137] op_sel:[0,1]
	v_cvt_pk_bf16_f32 v32, v32, v33
	v_cvt_pk_bf16_f32 v33, v36, v37
	v_cvt_pk_bf16_f32 v34, v34, v35
	v_cvt_pk_bf16_f32 v35, v138, v139
	v_cndmask_b32_e64 v135, 0, v178, s[26:27]
	v_cndmask_b32_e32 v37, v178, v135, vcc
	v_mfma_f32_32x32x16_bf16 v[0:15], v[80:83], v[32:35], v[0:15]
	v_mul_f32_e32 v36, v131, v185
	v_mul_f32_e32 v37, v37, v184
	v_mul_f32_e32 v40, v36, v37
	v_mul_f32_e32 v37, v44, v183
	v_mul_f32_e32 v158, v38, v182
	v_mov_b32_e32 v44, v42
	v_pk_mul_f32 v[46:47], v[46:47], v[42:43] op_sel:[0,1]
	v_mfma_f32_32x32x16_bf16 v[16:31], v[88:91], v[32:35], v[16:31]
	v_mul_f32_e32 v41, v36, v37
	v_pk_mul_f32 v[36:37], v[36:37], v[158:159] op_sel_hi:[0,1]
	v_pk_mul_f32 v[32:33], v[44:45], v[42:43] op_sel:[0,1]
	v_cvt_pk_bf16_f32 v34, v40, v41
	v_cvt_pk_bf16_f32 v32, v32, v33
	v_cvt_pk_bf16_f32 v33, v46, v47
	v_cvt_pk_bf16_f32 v35, v36, v37
	v_mul_f32_e32 v36, v130, v155
	v_mul_f32_e32 v131, v36, v39
	v_mfma_f32_32x32x16_bf16 v[0:15], v[84:87], v[32:35], v[0:15]
	v_cmp_gt_f32_e32 vcc, s72, v131
	s_cmp_eq_u64 vcc, exec
	s_cselect_b64 s[96:97], -1, 0
	s_or_b64 s[82:83], s[96:97], s[82:83]
	s_and_b64 vcc, exec, s[82:83]
	v_mfma_f32_32x32x16_bf16 v[16:31], v[92:95], v[32:35], v[16:31]
	s_cbranch_vccz .LBB0_111
	s_or_b64 s[84:85], s[96:97], s[84:85]
	s_andn2_b64 vcc, exec, s[82:83]
	s_cbranch_vccnz .LBB0_112
.LBB0_114:
	s_waitcnt vmcnt(0)
	s_mov_b64 s[96:97], 0x800
	s_or_b64 s[42:43], s[44:45], s[84:85]
	s_lshl_b32 s82, s75, 6
	s_and_b64 vcc, exec, s[42:43]
	s_cbranch_vccnz .LBB0_117
